# B (differential attention) steady-state tile loop hand-rewritten: QK MFMA accumulator starts from -m splat (no v_sub), plain row-sum adds, half-sum deferred to loop exit
# speedup vs baseline: 1.0343x; 1.0343x over previous
; DI void attn_diff_unit(int ub, int Ssh, float lam, float post, const float* subg, const bf16_t* PROJ, bf16_t* O, LAS unsigned char* lds, int wid, int lane) {
;     ...
;         qk64<2, 0>(pa0, pa1, cur, qr, r32, hi);
;         qk64<2, 2>(pb0, pb1, cur, qr, r32, hi);
;         const float mxA = xhalf_max(rowmax32(pa0, pa1)), mxB = xhalf_max(rowmax32(pb0, pb1));
;         if (t == 0 || __any(mxA > mA + 8.0f || mxB > mB + 8.0f)) {
;             const float nA = (t == 0) ? mxA : max2f(mA, mxA), nB = (t == 0) ? mxB : max2f(mB, mxB);
;             const float fA = fexp2(mA - nA), fB = fexp2(mB - nB); mA = nA; mB = nB; lA *= fA; lB *= fB;
; #pragma unroll
;             for (int r = 0; r < 16; ++r) { a0[r] *= fA; a1[r] *= fA; b0[r] *= fB; b1[r] *= fB; }
;         }
;         float sA = 0.f, sB = 0.f;
; #pragma unroll
;         for (int r = 0; r < 16; ++r) { pa0[r] = fexp2(pa0[r] - mA); pa1[r] = fexp2(pa1[r] - mA); sA += pa0[r] + pa1[r]; }
;         pwA[0] = (u32x4){cvtpk(pa0[0], pa0[1]), cvtpk(pa0[2], pa0[3]), cvtpk(pa0[4], pa0[5]), cvtpk(pa0[6], pa0[7])};
;         pwA[1] = (u32x4){cvtpk(pa0[8], pa0[9]), cvtpk(pa0[10], pa0[11]), cvtpk(pa0[12], pa0[13]), cvtpk(pa0[14], pa0[15])};
;         pwA[2] = (u32x4){cvtpk(pa1[0], pa1[1]), cvtpk(pa1[2], pa1[3]), cvtpk(pa1[4], pa1[5]), cvtpk(pa1[6], pa1[7])};
;         pwA[3] = (u32x4){cvtpk(pa1[8], pa1[9]), cvtpk(pa1[10], pa1[11]), cvtpk(pa1[12], pa1[13]), cvtpk(pa1[14], pa1[15])};
;         LAS const unsigned char* vp = cur + 8192 + vlane;
; #pragma unroll
;         for (int ks = 0; ks < 4; ++ks) {
;             const s16x4 lo0 = vtr(vp + ks * 1024), hi0 = vtr(vp + ks * 1024 + 512), lo1 = vtr(vp + 4096 + ks * 1024), hi1 = vtr(vp + 4096 + ks * 1024 + 512);
;             const bf16x8 v0 = (bf16x8){lo0[0], lo0[1], lo0[2], lo0[3], hi0[0], hi0[1], hi0[2], hi0[3]};
;             const bf16x8 v1 = (bf16x8){lo1[0], lo1[1], lo1[2], lo1[3], hi1[0], hi1[1], hi1[2], hi1[3]};
;             const bf16x8 pa = __builtin_bit_cast(bf16x8, pwA[ks]);
;             a0 = __builtin_amdgcn_mfma_f32_32x32x16_bf16(v0, pa, a0, 0, 0, 0);
;             a1 = __builtin_amdgcn_mfma_f32_32x32x16_bf16(v1, pa, a1, 0, 0, 0);
; #pragma unroll
;             for (int r = 4 * ks; r < 4 * ks + 4; ++r) { pb0[r] = fexp2(pb0[r] - mB); pb1[r] = fexp2(pb1[r] - mB); sB += pb0[r] + pb1[r]; }
;         }
;         lA += xhalf_sum(sA); lB += xhalf_sum(sB);
.Lbt_entry:
	v_add3_u32 v168, v213, v212, v211
	v_add3_u32 v169, v215, v214, v211
	v_add3_u32 v200, v217, v216, v211
	v_add3_u32 v201, v219, v218, v211
	v_add3_u32 v224, v207, v208, v209
	v_add_u32_e32 v224, v224, v210
	v_or_b32_e32 v168, 0x4000, v168
	v_or_b32_e32 v169, 0x4000, v169
	v_or_b32_e32 v200, 0x4000, v200
	v_or_b32_e32 v201, 0x4000, v201
	v_or_b32_e32 v224, 0x4000, v224
	v_sub_f32_e32 v176, 0, v220
	v_mov_b32_e32 v177, v176
	v_mov_b32_e32 v178, v176
	v_mov_b32_e32 v179, v176
	v_mov_b32_e32 v180, v176
	v_mov_b32_e32 v181, v176
	v_mov_b32_e32 v182, v176
	v_mov_b32_e32 v183, v176
	v_mov_b32_e32 v184, v176
	v_mov_b32_e32 v185, v176
	v_mov_b32_e32 v186, v176
	v_mov_b32_e32 v187, v176
	v_mov_b32_e32 v188, v176
	v_mov_b32_e32 v189, v176
	v_mov_b32_e32 v190, v176
	v_mov_b32_e32 v191, v176
	v_sub_f32_e32 v0, 0, v221
	v_mov_b32_e32 v208, v0
	v_mov_b32_e32 v209, v0
	v_mov_b32_e32 v210, v0
	v_mov_b32_e32 v211, v0
	v_mov_b32_e32 v212, v0
	v_mov_b32_e32 v213, v0
	v_mov_b32_e32 v214, v0
	v_mov_b32_e32 v215, v0
	v_mov_b32_e32 v216, v0
	v_mov_b32_e32 v217, v0
	v_mov_b32_e32 v218, v0
	v_mov_b32_e32 v219, v0
	v_mov_b32_e32 v220, v0
	v_mov_b32_e32 v221, v0
	v_mov_b32_e32 v222, v0
	v_mov_b32_e32 v223, v0
	v_mul_f32_e32 v156, 0.5, v156
	v_mul_f32_e32 v157, 0.5, v157
.Lbt_loop:
	s_add_i32 s10, s10, 1
	s_cmp_lt_u32 s10, s39
	s_cselect_b64 s[2:3], -1, 0
	s_cbranch_scc0 .Lbt_nold
	global_load_dwordx4 v[146:149], v[158:159], off offset:-512
	global_load_dwordx4 v[150:153], v[158:159], off
.Lbt_nold:
	ds_read_b128 v[82:85], v168
	ds_read_b128 v[86:89], v169
	ds_read_b128 v[98:101], v168 offset:512
	ds_read_b128 v[102:105], v169 offset:512
	ds_read_b128 v[114:117], v200
	ds_read_b128 v[118:121], v201
	ds_read_b128 v[160:163], v200 offset:512
	ds_read_b128 v[164:167], v201 offset:512
	s_waitcnt lgkmcnt(6)
	v_mfma_f32_32x32x16_bf16 v[66:81], v[82:85], v[130:133], v[176:191]
	v_mfma_f32_32x32x16_bf16 v[66:81], v[86:89], v[134:137], v[66:81]
	s_waitcnt lgkmcnt(4)
	v_mfma_f32_32x32x16_bf16 v[82:97], v[98:101], v[130:133], v[176:191]
	v_mfma_f32_32x32x16_bf16 v[82:97], v[102:105], v[134:137], v[82:97]
	s_waitcnt lgkmcnt(2)
	v_mfma_f32_32x32x16_bf16 v[98:113], v[114:117], v[138:141], v[208:223]
	v_mfma_f32_32x32x16_bf16 v[98:113], v[118:121], v[142:145], v[98:113]
	s_waitcnt lgkmcnt(0)
	v_mfma_f32_32x32x16_bf16 v[114:129], v[160:163], v[138:141], v[208:223]
	v_mfma_f32_32x32x16_bf16 v[114:129], v[164:167], v[142:145], v[114:129]
	v_xor_b32_e32 v168, 0x4000, v168
	v_xor_b32_e32 v169, 0x4000, v169
	v_xor_b32_e32 v200, 0x4000, v200
	v_xor_b32_e32 v201, 0x4000, v201
	s_nop 1
	v_max3_f32 v192, v66, v67, v68
	v_max3_f32 v193, v69, v70, v71
	v_max3_f32 v192, v192, v72, v73
	v_max3_f32 v193, v193, v74, v75
	v_max3_f32 v192, v192, v76, v77
	v_max3_f32 v193, v193, v78, v79
	v_max3_f32 v192, v192, v80, v81
	v_max3_f32 v193, v193, v82, v83
	v_max3_f32 v192, v192, v84, v85
	v_max3_f32 v193, v193, v86, v87
	v_max3_f32 v192, v192, v88, v89
	v_max3_f32 v193, v193, v90, v91
	v_max3_f32 v192, v192, v92, v93
	v_max3_f32 v193, v193, v94, v95
	v_max3_f32 v192, v192, v96, v97
	v_max_f32_e32 v192, v192, v193
	v_max3_f32 v194, v98, v99, v100
	v_max3_f32 v195, v101, v102, v103
	v_max3_f32 v194, v194, v104, v105
	v_max3_f32 v195, v195, v106, v107
	v_max3_f32 v194, v194, v108, v109
	v_max3_f32 v195, v195, v110, v111
	v_max3_f32 v194, v194, v112, v113
	v_max3_f32 v195, v195, v114, v115
	v_max3_f32 v194, v194, v116, v117
	v_max3_f32 v195, v195, v118, v119
	v_max3_f32 v194, v194, v120, v121
	v_max3_f32 v195, v195, v122, v123
	v_max3_f32 v194, v194, v124, v125
	v_max3_f32 v195, v195, v126, v127
	v_max3_f32 v194, v194, v128, v129
	v_max_f32_e32 v194, v194, v195
	v_max_f32_e32 v196, v192, v194
	v_cmp_lt_f32_e32 vcc, 0x41000000, v196
	s_cbranch_vccnz .Lbt_rare
.Lbt_common:
	v_exp_f32_e32 v66, v66
	v_exp_f32_e32 v67, v67
	v_exp_f32_e32 v68, v68
	v_exp_f32_e32 v69, v69
	v_exp_f32_e32 v70, v70
	v_exp_f32_e32 v71, v71
	v_add_f32_e32 v197, v66, v67
	v_cvt_pk_bf16_f32 v66, v66, v67
	v_exp_f32_e32 v72, v72
	v_exp_f32_e32 v73, v73
	v_add_f32_e32 v156, v156, v68
	v_add_f32_e32 v197, v197, v69
	v_cvt_pk_bf16_f32 v67, v68, v69
	v_exp_f32_e32 v74, v74
	v_exp_f32_e32 v75, v75
	v_add_f32_e32 v156, v156, v70
	v_add_f32_e32 v197, v197, v71
	v_cvt_pk_bf16_f32 v68, v70, v71
	v_exp_f32_e32 v76, v76
	v_exp_f32_e32 v77, v77
	v_add_f32_e32 v156, v156, v72
	v_add_f32_e32 v197, v197, v73
	v_cvt_pk_bf16_f32 v69, v72, v73
	v_exp_f32_e32 v78, v78
	v_exp_f32_e32 v79, v79
	v_add_f32_e32 v156, v156, v74
	v_add_f32_e32 v197, v197, v75
	v_cvt_pk_bf16_f32 v70, v74, v75
	v_exp_f32_e32 v80, v80
	v_exp_f32_e32 v81, v81
	v_add_f32_e32 v156, v156, v76
	v_add_f32_e32 v197, v197, v77
	v_cvt_pk_bf16_f32 v71, v76, v77
	v_add_f32_e32 v156, v156, v78
	v_add_f32_e32 v197, v197, v79
	v_cvt_pk_bf16_f32 v72, v78, v79
	v_add_f32_e32 v156, v156, v80
	v_add_f32_e32 v197, v197, v81
	v_cvt_pk_bf16_f32 v73, v80, v81
	v_exp_f32_e32 v82, v82
	v_exp_f32_e32 v83, v83
	v_exp_f32_e32 v84, v84
	v_exp_f32_e32 v85, v85
	v_exp_f32_e32 v86, v86
	v_exp_f32_e32 v87, v87
	v_add_f32_e32 v156, v156, v82
	v_add_f32_e32 v197, v197, v83
	v_cvt_pk_bf16_f32 v82, v82, v83
	v_exp_f32_e32 v88, v88
	v_exp_f32_e32 v89, v89
	v_add_f32_e32 v156, v156, v84
	v_add_f32_e32 v197, v197, v85
	v_cvt_pk_bf16_f32 v83, v84, v85
	v_exp_f32_e32 v90, v90
	v_exp_f32_e32 v91, v91
	v_add_f32_e32 v156, v156, v86
	v_add_f32_e32 v197, v197, v87
	v_cvt_pk_bf16_f32 v84, v86, v87
	v_exp_f32_e32 v92, v92
	v_exp_f32_e32 v93, v93
	v_add_f32_e32 v156, v156, v88
	v_add_f32_e32 v197, v197, v89
	v_cvt_pk_bf16_f32 v85, v88, v89
	v_exp_f32_e32 v94, v94
	v_exp_f32_e32 v95, v95
	v_add_f32_e32 v156, v156, v90
	v_add_f32_e32 v197, v197, v91
	v_cvt_pk_bf16_f32 v86, v90, v91
	v_exp_f32_e32 v96, v96
	v_exp_f32_e32 v97, v97
	v_add_f32_e32 v156, v156, v92
	v_add_f32_e32 v197, v197, v93
	v_cvt_pk_bf16_f32 v87, v92, v93
	v_add_f32_e32 v156, v156, v94
	v_add_f32_e32 v197, v197, v95
	v_cvt_pk_bf16_f32 v88, v94, v95
	v_add_f32_e32 v156, v156, v96
	v_add_f32_e32 v197, v197, v97
	v_cvt_pk_bf16_f32 v89, v96, v97
	v_add_f32_e32 v156, v156, v197
	ds_read_b64_tr_b16 v[74:75], v224 offset:8192
	ds_read_b64_tr_b16 v[76:77], v224 offset:8704
	ds_read_b64_tr_b16 v[78:79], v224 offset:12288
	ds_read_b64_tr_b16 v[80:81], v224 offset:12800
	ds_read_b64_tr_b16 v[90:91], v224 offset:9216
	ds_read_b64_tr_b16 v[92:93], v224 offset:9728
	ds_read_b64_tr_b16 v[94:95], v224 offset:13312
	ds_read_b64_tr_b16 v[96:97], v224 offset:13824
	v_exp_f32_e32 v98, v98
	v_exp_f32_e32 v99, v99
	v_exp_f32_e32 v100, v100
	v_exp_f32_e32 v101, v101
	v_exp_f32_e32 v102, v102
	v_exp_f32_e32 v103, v103
	v_add_f32_e32 v198, v98, v99
	v_cvt_pk_bf16_f32 v98, v98, v99
	v_exp_f32_e32 v104, v104
	v_exp_f32_e32 v105, v105
	v_add_f32_e32 v157, v157, v100
	v_add_f32_e32 v198, v198, v101
	v_cvt_pk_bf16_f32 v99, v100, v101
	v_exp_f32_e32 v106, v106
	v_exp_f32_e32 v107, v107
	v_add_f32_e32 v157, v157, v102
	v_add_f32_e32 v198, v198, v103
	v_cvt_pk_bf16_f32 v100, v102, v103
	s_waitcnt lgkmcnt(0)
; DI void attn_diff_unit(int ub, int Ssh, float lam, float post, const float* subg, const bf16_t* PROJ, bf16_t* O, LAS unsigned char* lds, int wid, int lane) {
;     ...
;         for (int ks = 0; ks < 4; ++ks) {
;             const s16x4 lo0 = vtr(vp + ks * 1024), hi0 = vtr(vp + ks * 1024 + 512), lo1 = vtr(vp + 4096 + ks * 1024), hi1 = vtr(vp + 4096 + ks * 1024 + 512);
;             const bf16x8 v0 = (bf16x8){lo0[0], lo0[1], lo0[2], lo0[3], hi0[0], hi0[1], hi0[2], hi0[3]};
;             const bf16x8 v1 = (bf16x8){lo1[0], lo1[1], lo1[2], lo1[3], hi1[0], hi1[1], hi1[2], hi1[3]};
;             const bf16x8 pa = __builtin_bit_cast(bf16x8, pwA[ks]);
;             a0 = __builtin_amdgcn_mfma_f32_32x32x16_bf16(v0, pa, a0, 0, 0, 0);
;             a1 = __builtin_amdgcn_mfma_f32_32x32x16_bf16(v1, pa, a1, 0, 0, 0);
; #pragma unroll
;             for (int r = 4 * ks; r < 4 * ks + 4; ++r) { pb0[r] = fexp2(pb0[r] - mB); pb1[r] = fexp2(pb1[r] - mB); sB += pb0[r] + pb1[r]; }
;         }
;         lA += xhalf_sum(sA); lB += xhalf_sum(sB);
;         pwB[0] = (u32x4){cvtpk(pb0[0], pb0[1]), cvtpk(pb0[2], pb0[3]), cvtpk(pb0[4], pb0[5]), cvtpk(pb0[6], pb0[7])};
;         pwB[1] = (u32x4){cvtpk(pb0[8], pb0[9]), cvtpk(pb0[10], pb0[11]), cvtpk(pb0[12], pb0[13]), cvtpk(pb0[14], pb0[15])};
;         pwB[2] = (u32x4){cvtpk(pb1[0], pb1[1]), cvtpk(pb1[2], pb1[3]), cvtpk(pb1[4], pb1[5]), cvtpk(pb1[6], pb1[7])};
;         pwB[3] = (u32x4){cvtpk(pb1[8], pb1[9]), cvtpk(pb1[10], pb1[11]), cvtpk(pb1[12], pb1[13]), cvtpk(pb1[14], pb1[15])};
; #pragma unroll
;         for (int ks = 0; ks < 4; ++ks) {
;             const s16x4 lo0 = vtr(vp + ks * 1024), hi0 = vtr(vp + ks * 1024 + 512), lo1 = vtr(vp + 4096 + ks * 1024), hi1 = vtr(vp + 4096 + ks * 1024 + 512);
;             const bf16x8 v0 = (bf16x8){lo0[0], lo0[1], lo0[2], lo0[3], hi0[0], hi0[1], hi0[2], hi0[3]};
;             const bf16x8 v1 = (bf16x8){lo1[0], lo1[1], lo1[2], lo1[3], hi1[0], hi1[1], hi1[2], hi1[3]};
;             const bf16x8 pb = __builtin_bit_cast(bf16x8, pwB[ks]);
;             b0 = __builtin_amdgcn_mfma_f32_32x32x16_bf16(v0, pb, b0, 0, 0, 0);
;             b1 = __builtin_amdgcn_mfma_f32_32x32x16_bf16(v1, pb, b1, 0, 0, 0);
;         }
;     };
;     for (int t = 0; t < NT; ++t) {
;         LAS unsigned char* cur = lds + (t & 1) * 16384; LAS unsigned char* nxt = lds + ((t + 1) & 1) * 16384;
	v_mfma_f32_32x32x16_bf16 v[34:49], v[74:77], v[66:69], v[34:49]
	v_exp_f32_e32 v108, v108
	v_exp_f32_e32 v109, v109
	v_add_f32_e32 v157, v157, v104
	v_add_f32_e32 v198, v198, v105
	v_cvt_pk_bf16_f32 v101, v104, v105
	v_mfma_f32_32x32x16_bf16 v[2:17], v[78:81], v[66:69], v[2:17]
	v_exp_f32_e32 v110, v110
	v_exp_f32_e32 v111, v111
	v_add_f32_e32 v157, v157, v106
	v_add_f32_e32 v198, v198, v107
	v_cvt_pk_bf16_f32 v102, v106, v107
	v_mfma_f32_32x32x16_bf16 v[34:49], v[90:93], v[70:73], v[34:49]
	v_exp_f32_e32 v112, v112
	v_exp_f32_e32 v113, v113
	v_add_f32_e32 v157, v157, v108
	v_add_f32_e32 v198, v198, v109
	v_cvt_pk_bf16_f32 v103, v108, v109
	v_mfma_f32_32x32x16_bf16 v[2:17], v[94:97], v[70:73], v[2:17]
	v_add_f32_e32 v157, v157, v110
	v_add_f32_e32 v198, v198, v111
	v_cvt_pk_bf16_f32 v104, v110, v111
	ds_read_b64_tr_b16 v[74:75], v224 offset:10240
	ds_read_b64_tr_b16 v[76:77], v224 offset:10752
	ds_read_b64_tr_b16 v[78:79], v224 offset:14336
	ds_read_b64_tr_b16 v[80:81], v224 offset:14848
	ds_read_b64_tr_b16 v[90:91], v224 offset:11264
	ds_read_b64_tr_b16 v[92:93], v224 offset:11776
	ds_read_b64_tr_b16 v[94:95], v224 offset:15360
	ds_read_b64_tr_b16 v[96:97], v224 offset:15872
	v_add_f32_e32 v157, v157, v112
	v_add_f32_e32 v198, v198, v113
	v_cvt_pk_bf16_f32 v105, v112, v113
	v_exp_f32_e32 v114, v114
	v_exp_f32_e32 v115, v115
	v_exp_f32_e32 v116, v116
	v_exp_f32_e32 v117, v117
	v_exp_f32_e32 v118, v118
	v_exp_f32_e32 v119, v119
	v_add_f32_e32 v157, v157, v114
	v_add_f32_e32 v198, v198, v115
	v_cvt_pk_bf16_f32 v114, v114, v115
	v_exp_f32_e32 v120, v120
	v_exp_f32_e32 v121, v121
	v_add_f32_e32 v157, v157, v116
	v_add_f32_e32 v198, v198, v117
	s_waitcnt lgkmcnt(0)
	v_mfma_f32_32x32x16_bf16 v[34:49], v[74:77], v[82:85], v[34:49]
	v_cvt_pk_bf16_f32 v115, v116, v117
	v_exp_f32_e32 v122, v122
	v_exp_f32_e32 v123, v123
	v_add_f32_e32 v157, v157, v118
	v_add_f32_e32 v198, v198, v119
	v_mfma_f32_32x32x16_bf16 v[2:17], v[78:81], v[82:85], v[2:17]
	v_cvt_pk_bf16_f32 v116, v118, v119
	v_exp_f32_e32 v124, v124
	v_exp_f32_e32 v125, v125
	v_add_f32_e32 v157, v157, v120
	v_add_f32_e32 v198, v198, v121
	v_mfma_f32_32x32x16_bf16 v[34:49], v[90:93], v[86:89], v[34:49]
	v_cvt_pk_bf16_f32 v117, v120, v121
	v_exp_f32_e32 v126, v126
	v_exp_f32_e32 v127, v127
	v_add_f32_e32 v157, v157, v122
	v_add_f32_e32 v198, v198, v123
	v_mfma_f32_32x32x16_bf16 v[2:17], v[94:97], v[86:89], v[2:17]
	v_cvt_pk_bf16_f32 v118, v122, v123
	v_exp_f32_e32 v128, v128
	v_exp_f32_e32 v129, v129
	ds_read_b64_tr_b16 v[66:67], v224 offset:8192
	ds_read_b64_tr_b16 v[68:69], v224 offset:8704
	ds_read_b64_tr_b16 v[70:71], v224 offset:12288
	ds_read_b64_tr_b16 v[72:73], v224 offset:12800
	ds_read_b64_tr_b16 v[74:75], v224 offset:9216
	ds_read_b64_tr_b16 v[76:77], v224 offset:9728
	ds_read_b64_tr_b16 v[78:79], v224 offset:13312
	ds_read_b64_tr_b16 v[80:81], v224 offset:13824
	ds_read_b64_tr_b16 v[82:83], v224 offset:10240
	ds_read_b64_tr_b16 v[84:85], v224 offset:10752
	ds_read_b64_tr_b16 v[86:87], v224 offset:14336
	ds_read_b64_tr_b16 v[88:89], v224 offset:14848
	ds_read_b64_tr_b16 v[90:91], v224 offset:11264
	ds_read_b64_tr_b16 v[92:93], v224 offset:11776
	ds_read_b64_tr_b16 v[94:95], v224 offset:15360
	ds_read_b64_tr_b16 v[96:97], v224 offset:15872
	v_add_f32_e32 v157, v157, v124
	v_add_f32_e32 v198, v198, v125
	v_cvt_pk_bf16_f32 v119, v124, v125
	v_add_f32_e32 v157, v157, v126
	v_add_f32_e32 v198, v198, v127
	v_cvt_pk_bf16_f32 v120, v126, v127
	v_add_f32_e32 v157, v157, v128
	v_add_f32_e32 v198, v198, v129
	v_cvt_pk_bf16_f32 v121, v128, v129
	v_add_f32_e32 v157, v157, v198
	s_nop 0
	s_waitcnt lgkmcnt(0)
	v_mfma_f32_32x32x16_bf16 v[50:65], v[66:69], v[98:101], v[50:65]
	v_mfma_f32_32x32x16_bf16 v[18:33], v[70:73], v[98:101], v[18:33]
	v_mfma_f32_32x32x16_bf16 v[50:65], v[74:77], v[102:105], v[50:65]
	v_mfma_f32_32x32x16_bf16 v[18:33], v[78:81], v[102:105], v[18:33]
	v_mfma_f32_32x32x16_bf16 v[50:65], v[82:85], v[114:117], v[50:65]
	v_mfma_f32_32x32x16_bf16 v[18:33], v[86:89], v[114:117], v[18:33]
	v_mfma_f32_32x32x16_bf16 v[50:65], v[90:93], v[118:121], v[50:65]
	v_mfma_f32_32x32x16_bf16 v[18:33], v[94:97], v[118:121], v[18:33]
	s_andn2_b64 vcc, exec, s[2:3]
	s_cbranch_vccnz .Lbt_nowr
	s_waitcnt vmcnt(1)
	ds_write_b128 v205, v[146:149]
	s_waitcnt vmcnt(0)
	ds_write_b128 v206, v[150:153] offset:8192
.Lbt_nowr:
	v_xor_b32_e32 v205, 0x4000, v205
	v_xor_b32_e32 v206, 0x4000, v206
	v_xor_b32_e32 v224, 0x4000, v224
	s_mov_b64 s[0:1], 0x62000
	v_lshl_add_u64 v[158:159], v[158:159], 0, s[0:1]
	s_cmp_lg_u32 s39, s10
	s_waitcnt lgkmcnt(0)
	s_barrier
	s_cbranch_scc1 .Lbt_loop
	v_mov_b32_e32 v192, v156
	v_mov_b32_e32 v193, v157
	s_nop 1
	v_permlane32_swap_b32_e32 v156, v192
	v_permlane32_swap_b32_e32 v157, v193
	v_add_f32_e32 v156, v156, v192
	v_add_f32_e32 v157, v157, v193
	s_branch .LBB0_514
; DI float fexp2(float x) { return __builtin_amdgcn_exp2f(x); }
; DI float max2f(float a, float b) { float r; asm("v_max_f32_e32 %0, %1, %2" : "=v"(r) : "v"(a), "v"(b)); return r; }
; DI void attn_diff_unit(int ub, int Ssh, float lam, float post, const float* subg, const bf16_t* PROJ, bf16_t* O, LAS unsigned char* lds, int wid, int lane) {
;     ...
;         if (t == 0 || __any(mxA > mA + 8.0f || mxB > mB + 8.0f)) {
;             const float nA = (t == 0) ? mxA : max2f(mA, mxA), nB = (t == 0) ? mxB : max2f(mB, mxB);
;             const float fA = fexp2(mA - nA), fB = fexp2(mB - nB); mA = nA; mB = nB; lA *= fA; lB *= fB;
; #pragma unroll
;             for (int r = 0; r < 16; ++r) { a0[r] *= fA; a1[r] *= fA; b0[r] *= fB; b1[r] *= fB; }
;         }
.Lbt_rare:
	v_mov_b32_e32 v193, v192
	v_mov_b32_e32 v195, v194
	s_nop 1
	v_permlane32_swap_b32_e32 v192, v193
	v_permlane32_swap_b32_e32 v194, v195
	v_max_f32_e32 v192, v192, v193
	v_max_f32_e32 v194, v194, v195
	v_max_f32_e32 v192, 0, v192
	v_max_f32_e32 v194, 0, v194
	v_exp_f32_e64 v193, -v192
	v_exp_f32_e64 v195, -v194
	v_sub_f32_e32 v176, v176, v192
	v_sub_f32_e32 v177, v177, v192
	v_sub_f32_e32 v178, v178, v192
	v_sub_f32_e32 v179, v179, v192
	v_sub_f32_e32 v180, v180, v192
	v_sub_f32_e32 v181, v181, v192
	v_sub_f32_e32 v182, v182, v192
	v_sub_f32_e32 v183, v183, v192
	v_sub_f32_e32 v184, v184, v192
	v_sub_f32_e32 v185, v185, v192
	v_sub_f32_e32 v186, v186, v192
	v_sub_f32_e32 v187, v187, v192
	v_sub_f32_e32 v188, v188, v192
	v_sub_f32_e32 v189, v189, v192
	v_sub_f32_e32 v190, v190, v192
	v_sub_f32_e32 v191, v191, v192
	v_sub_f32_e32 v208, v208, v194
	v_sub_f32_e32 v209, v209, v194
	v_sub_f32_e32 v210, v210, v194
	v_sub_f32_e32 v211, v211, v194
	v_sub_f32_e32 v212, v212, v194
	v_sub_f32_e32 v213, v213, v194
	v_sub_f32_e32 v214, v214, v194
	v_sub_f32_e32 v215, v215, v194
	v_sub_f32_e32 v216, v216, v194
	v_sub_f32_e32 v217, v217, v194
	v_sub_f32_e32 v218, v218, v194
	v_sub_f32_e32 v219, v219, v194
	v_sub_f32_e32 v220, v220, v194
	v_sub_f32_e32 v221, v221, v194
	v_sub_f32_e32 v222, v222, v194
	v_sub_f32_e32 v223, v223, v194
	v_sub_f32_e32 v66, v66, v192
	v_sub_f32_e32 v67, v67, v192
	v_sub_f32_e32 v68, v68, v192
	v_sub_f32_e32 v69, v69, v192
	v_sub_f32_e32 v70, v70, v192
	v_sub_f32_e32 v71, v71, v192
	v_sub_f32_e32 v72, v72, v192
	v_sub_f32_e32 v73, v73, v192
	v_sub_f32_e32 v74, v74, v192
	v_sub_f32_e32 v75, v75, v192
	v_sub_f32_e32 v76, v76, v192
	v_sub_f32_e32 v77, v77, v192
	v_sub_f32_e32 v78, v78, v192
	v_sub_f32_e32 v79, v79, v192
	v_sub_f32_e32 v80, v80, v192
	v_sub_f32_e32 v81, v81, v192
	v_sub_f32_e32 v82, v82, v192
	v_sub_f32_e32 v83, v83, v192
	v_sub_f32_e32 v84, v84, v192
	v_sub_f32_e32 v85, v85, v192
	v_sub_f32_e32 v86, v86, v192
	v_sub_f32_e32 v87, v87, v192
	v_sub_f32_e32 v88, v88, v192
	v_sub_f32_e32 v89, v89, v192
	v_sub_f32_e32 v90, v90, v192
	v_sub_f32_e32 v91, v91, v192
	v_sub_f32_e32 v92, v92, v192
	v_sub_f32_e32 v93, v93, v192
	v_sub_f32_e32 v94, v94, v192
	v_sub_f32_e32 v95, v95, v192
	v_sub_f32_e32 v96, v96, v192
	v_sub_f32_e32 v97, v97, v192
	v_sub_f32_e32 v98, v98, v194
	v_sub_f32_e32 v99, v99, v194
	v_sub_f32_e32 v100, v100, v194
	v_sub_f32_e32 v101, v101, v194
	v_sub_f32_e32 v102, v102, v194
	v_sub_f32_e32 v103, v103, v194
	v_sub_f32_e32 v104, v104, v194
	v_sub_f32_e32 v105, v105, v194
	v_sub_f32_e32 v106, v106, v194
	v_sub_f32_e32 v107, v107, v194
	v_sub_f32_e32 v108, v108, v194
	v_sub_f32_e32 v109, v109, v194
	v_sub_f32_e32 v110, v110, v194
	v_sub_f32_e32 v111, v111, v194
	v_sub_f32_e32 v112, v112, v194
	v_sub_f32_e32 v113, v113, v194
	v_sub_f32_e32 v114, v114, v194
	v_sub_f32_e32 v115, v115, v194
	v_sub_f32_e32 v116, v116, v194
	v_sub_f32_e32 v117, v117, v194
	v_sub_f32_e32 v118, v118, v194
	v_sub_f32_e32 v119, v119, v194
	v_sub_f32_e32 v120, v120, v194
	v_sub_f32_e32 v121, v121, v194
	v_sub_f32_e32 v122, v122, v194
	v_sub_f32_e32 v123, v123, v194
	v_sub_f32_e32 v124, v124, v194
	v_sub_f32_e32 v125, v125, v194
	v_sub_f32_e32 v126, v126, v194
	v_sub_f32_e32 v127, v127, v194
	v_sub_f32_e32 v128, v128, v194
	v_sub_f32_e32 v129, v129, v194
	v_mul_f32_e32 v156, v156, v193
	v_mul_f32_e32 v157, v157, v195
	v_mul_f32_e32 v34, v34, v193
	v_mul_f32_e32 v35, v35, v193
	v_mul_f32_e32 v36, v36, v193
	v_mul_f32_e32 v37, v37, v193
	v_mul_f32_e32 v38, v38, v193
	v_mul_f32_e32 v39, v39, v193
	v_mul_f32_e32 v40, v40, v193
	v_mul_f32_e32 v41, v41, v193
	v_mul_f32_e32 v42, v42, v193
	v_mul_f32_e32 v43, v43, v193
	v_mul_f32_e32 v44, v44, v193
	v_mul_f32_e32 v45, v45, v193
	v_mul_f32_e32 v46, v46, v193
	v_mul_f32_e32 v47, v47, v193
	v_mul_f32_e32 v48, v48, v193
	v_mul_f32_e32 v49, v49, v193
	v_mul_f32_e32 v2, v2, v193
	v_mul_f32_e32 v3, v3, v193
	v_mul_f32_e32 v4, v4, v193
	v_mul_f32_e32 v5, v5, v193
	v_mul_f32_e32 v6, v6, v193
	v_mul_f32_e32 v7, v7, v193
	v_mul_f32_e32 v8, v8, v193
	v_mul_f32_e32 v9, v9, v193
	v_mul_f32_e32 v10, v10, v193
	v_mul_f32_e32 v11, v11, v193
	v_mul_f32_e32 v12, v12, v193
	v_mul_f32_e32 v13, v13, v193
	v_mul_f32_e32 v14, v14, v193
	v_mul_f32_e32 v15, v15, v193
	v_mul_f32_e32 v16, v16, v193
	v_mul_f32_e32 v17, v17, v193
	v_mul_f32_e32 v50, v50, v195
	v_mul_f32_e32 v51, v51, v195
	v_mul_f32_e32 v52, v52, v195
	v_mul_f32_e32 v53, v53, v195
	v_mul_f32_e32 v54, v54, v195
	v_mul_f32_e32 v55, v55, v195
	v_mul_f32_e32 v56, v56, v195
	v_mul_f32_e32 v57, v57, v195
	v_mul_f32_e32 v58, v58, v195
	v_mul_f32_e32 v59, v59, v195
	v_mul_f32_e32 v60, v60, v195
	v_mul_f32_e32 v61, v61, v195
	v_mul_f32_e32 v62, v62, v195
	v_mul_f32_e32 v63, v63, v195
	v_mul_f32_e32 v64, v64, v195
	v_mul_f32_e32 v65, v65, v195
	v_mul_f32_e32 v18, v18, v195
	v_mul_f32_e32 v19, v19, v195
	v_mul_f32_e32 v20, v20, v195
	v_mul_f32_e32 v21, v21, v195
	v_mul_f32_e32 v22, v22, v195
	v_mul_f32_e32 v23, v23, v195
	v_mul_f32_e32 v24, v24, v195
	v_mul_f32_e32 v25, v25, v195
	v_mul_f32_e32 v26, v26, v195
	v_mul_f32_e32 v27, v27, v195
	v_mul_f32_e32 v28, v28, v195
	v_mul_f32_e32 v29, v29, v195
	v_mul_f32_e32 v30, v30, v195
	v_mul_f32_e32 v31, v31, v195
	v_mul_f32_e32 v32, v32, v195
	v_mul_f32_e32 v33, v33, v195
	s_branch .Lbt_common
